# static s_setprio 1 for the younger wave half (waves 4-7) over the phase-8 gla_c item loop (two waves per SIMD, MFMA + VALU), reset at the loop exit
# speedup vs baseline: 1.0070x; 1.0070x over previous
; __device__ __forceinline__ void gla_c_item(const Params& P, int item, unsigned char* smem) {
;     float* sGLR = (float*)smem;
;     float* sPart = (float*)(smem + 8192);
;     bf16_t* sQD = (bf16_t*)(smem + 10240);
;     bf16_t* sKD = (bf16_t*)(smem + 10240 + 9216);
;     bf16_t* sQG = (bf16_t*)(smem + 10240 + 2 * 9216);
;     bf16_t* sP = (bf16_t*)(smem + 10240 + 2 * 9216 + 17408);
;     bf16_t* sVt = (bf16_t*)(smem + 10240 + 3 * 9216 + 17408);
;     const int m = item & 127, h = (item >> 7) & 3, b = item >> 9;
;     const int rowbase = b * 8192 + m * 64;
;     const bf16_t* Q = (const bf16_t*)(P.ws + OFF_Q); const bf16_t* Kb = (const bf16_t*)(P.ws + OFF_K);
;     bf16_t* V = (bf16_t*)(P.ws + OFF_V); const bf16_t* R = (const bf16_t*)(P.ws + OFF_R); const bf16_t* GLR = (const bf16_t*)(P.ws + OFF_GLR);
;     const int tid = threadIdx.x & 255, lane = tid & 63, w = tid >> 6, fr = lane & 15, fq = lane >> 4, dk = tid & 63, part = tid >> 6;
;     const VRegs vr = load_v_regs(V + (size_t)rowbase * 512 + h * 128, tid);
;     const uint4 gl8 = *(const uint4*)(GLR + (size_t)(rowbase + (tid >> 2)) * 32 + (tid & 3) * 8);
;     float qq[16], kk[16];
; #pragma unroll
;     for (int ii = 0; ii < 16; ++ii) { qq[ii] = bf2f(Q[(size_t)(rowbase + part * 16 + ii) * 256 + h * 64 + dk]); kk[ii] = bf2f(Kb[(size_t)(rowbase + part * 16 + ii) * 256 + h * 64 + dk]); }
;     const GateW gw0 = load_gate_w(P, 0, h, dk), gw1 = load_gate_w(P, 1, h, dk);
;     {
;         float* gp = sGLR + (tid >> 2) * 32 + (tid & 3) * 8;
;         *(f32x4*)gp = (f32x4){bflo(gl8.x), bfhi(gl8.x), bflo(gl8.y), bfhi(gl8.y)};
;         *(f32x4*)(gp + 4) = (f32x4){bflo(gl8.z), bfhi(gl8.z), bflo(gl8.w), bfhi(gl8.w)};
;     }
;     store_vt(vr, sVt, tid);
;     __syncthreads();
;     float gc0[16], gc1[16];
;     { const float tot0 = gate_prefix(gw0, sGLR, 32, 0, part, gc0); const float tot1 = gate_prefix(gw1, sGLR + 16, 32, 1, part, gc1);
;       sPart[part * 64 + dk] = tot0; sPart[256 + part * 64 + dk] = tot1; }
;     __syncthreads();
;     float gref0, gref1;
;     {
;         const float a0 = sPart[dk], a1 = sPart[64 + dk], a2 = sPart[128 + dk];
;         const float c1 = sPart[256 + 64 + dk], c2 = sPart[256 + 128 + dk], c3 = sPart[256 + 192 + dk];
;         const float off0 = part == 0 ? 0.f : (part == 1 ? a0 : (part == 2 ? a0 + a1 : a0 + a1 + a2));
.LBB0_1317:
.LBB0_1318:
	v_lshlrev_b32_e32 v4, 3, v168
	v_lshrrev_b32_e32 v88, 8, v168
	s_mov_b32 s0, 0x13800
	v_bfe_u32 v90, v168, 2, 6
	v_and_b32_e32 v5, 24, v4
	s_waitcnt lgkmcnt(0)
	v_mad_u32_u24 v1, v88, s0, 16
	v_lshrrev_b32_e32 v75, 1, v168
	v_lshlrev_b32_e32 v4, 7, v90
	v_lshlrev_b32_e32 v6, 2, v5
	v_bfe_u32 v89, v168, 6, 2
	v_and_b32_e32 v2, 0x70, v75
	v_add3_u32 v92, v1, v4, v6
	v_lshlrev_b32_e32 v6, 2, v168
	v_lshlrev_b32_e32 v91, 4, v89
	v_mul_u32_u24_e32 v4, 0x90, v2
	v_and_b32_e32 v6, 0x7c, v6
	v_and_b32_e32 v169, 15, v168
	v_and_b32_e32 v3, 0xff, v168
	v_add3_u32 v93, v1, v4, v6
	v_or_b32_e32 v97, v91, v169
	v_and_b32_e32 v4, 48, v168
	v_lshl_add_u32 v95, v3, 2, v1
	v_cmp_lt_u32_e64 s[74:75], 63, v3
	v_mul_u32_u24_e32 v3, 0x48, v97
	v_add_u32_e32 v7, v1, v4
	v_lshl_add_u32 v98, v3, 1, v7
	v_mul_u32_u24_e32 v3, 0x480, v89
	v_lshl_add_u32 v96, v170, 2, v1
	v_or_b32_e32 v3, v3, v170
	v_lshlrev_b32_e32 v6, 1, v170
	v_lshl_add_u32 v99, v3, 1, v1
	v_mul_u32_u24_e32 v3, 0x880, v89
	v_sub_u32_e32 v6, v96, v6
	v_lshl_add_u32 v100, v3, 1, v6
	v_or_b32_e32 v3, 1, v91
	v_mul_u32_u24_e32 v8, 0x48, v3
	v_lshl_add_u32 v101, v8, 1, v6
	v_mul_u32_u24_e32 v8, 0x88, v3
	s_movk_i32 s0, 0x48
	v_lshl_add_u32 v102, v8, 1, v6
	v_mov_b32_e32 v8, 0x1f8
	v_mad_u32_u24 v3, v3, s0, v8
	v_lshrrev_b32_e32 v10, 2, v168
	v_or_b32_e32 v8, v3, v170
	v_lshl_add_u32 v3, v3, 1, v6
	v_and_b32_e32 v6, 12, v10
	v_or_b32_e32 v11, v91, v6
	v_writelane_b32 v251, s88, 54
	v_or_b32_e32 v9, 48, v169
	v_or_b32_e32 v13, 2, v11
	v_writelane_b32 v251, s89, 55
	v_cmp_lt_u32_e64 s[2:3], v9, v13
	v_or_b32_e32 v15, 1, v11
	s_add_u32 s78, s68, 0xd0bd000
	v_writelane_b32 v251, s2, 5
	v_lshl_add_u32 v115, v8, 1, v1
	v_or_b32_e32 v8, 32, v169
	v_writelane_b32 v251, s3, 6
	v_cmp_gt_u32_e64 s[2:3], v9, v13
	v_or_b32_e32 v12, 3, v11
	s_addc_u32 s79, s69, 0
	v_writelane_b32 v251, s2, 56
	s_add_u32 s80, s68, 0xe13d000
	v_add_u32_e32 v117, 0x90, v3
	v_writelane_b32 v251, s3, 57
	v_cmp_gt_u32_e64 s[2:3], v9, v15
	v_add_u32_e32 v119, 0x120, v3
	v_add_u32_e32 v121, 0x1b0, v3
	v_writelane_b32 v251, s2, 58
	v_add_u32_e32 v123, 0x240, v3
	v_add_u32_e32 v125, 0x2d0, v3
	v_writelane_b32 v251, s3, 59
	v_cmp_lt_u32_e64 s[2:3], v9, v11
	v_add_u32_e32 v127, 0x360, v3
	v_add_u32_e32 v129, 0x3f0, v3
	v_writelane_b32 v251, s2, 60
	v_mul_u32_u24_e32 v3, 0x48, v169
	s_addc_u32 s81, s69, 0
	v_writelane_b32 v251, s3, 61
	v_cmp_lt_u32_e64 s[2:3], v8, v12
	v_lshl_add_u32 v131, v3, 1, v7
	v_or_b32_e32 v3, 16, v169
	v_writelane_b32 v251, s2, 62
	s_add_u32 s82, s68, 0xf1bd000
	v_cmp_lt_u32_e64 s[30:31], v3, v12
	v_writelane_b32 v251, s3, 63
	v_cmp_gt_u32_e64 s[2:3], v8, v12
	v_cmp_gt_u32_e64 s[34:35], v3, v12
	v_cmp_lt_u32_e64 s[36:37], v3, v13
	v_writelane_b32 v250, s2, 0
	v_cmp_gt_u32_e64 s[38:39], v3, v13
	v_cmp_gt_u32_e64 s[40:41], v3, v11
	v_cmp_gt_u32_e64 s[42:43], v3, v15
	v_cmp_lt_u32_e64 s[44:45], v3, v11
	v_mul_u32_u24_e32 v3, 0x48, v11
	s_addc_u32 s83, s69, 0
	v_lshlrev_b32_e32 v0, 10, v168
	v_mov_b32_e32 v37, 0
	s_movk_i32 s1, 0x110
	v_writelane_b32 v250, s3, 1
	v_cmp_lt_u32_e64 s[2:3], v8, v13
	v_cmp_gt_u32_e64 s[6:7], v8, v13
	v_cmp_gt_u32_e64 s[24:25], v8, v11
	v_cmp_gt_u32_e64 s[26:27], v8, v15
	v_cmp_lt_u32_e64 s[28:29], v8, v11
	v_lshlrev_b32_e32 v8, 1, v169
	v_lshlrev_b32_e32 v3, 1, v3
	v_lshlrev_b32_e32 v36, 1, v5
	s_add_u32 s84, s68, 0x112bd000
	v_and_b32_e32 v0, 0x7c00, v0
	v_lshl_add_u32 v94, v89, 11, v1
	v_add3_u32 v132, v1, v8, v3
	v_and_or_b32 v1, v10, 64, v97
	v_mad_u32_u24 v137, v97, s1, v7
	v_lshlrev_b32_e32 v8, 6, v169
	v_lshl_add_u64 v[22:23], s[68:69], 0, v[36:37]
	s_mov_b64 s[0:1], 0x133bd000
	s_addc_u32 s85, s69, 0
	v_mov_b32_e32 v5, v37
	v_readlane_b32 s8, v251, 37
	v_cmp_lt_u32_e64 s[86:87], v9, v12
	v_cmp_gt_u32_e64 s[94:95], v9, v12
	v_writelane_b32 v250, s2, 2
	v_cmp_lt_u32_e64 s[46:47], v169, v12
	v_cmp_gt_u32_e64 s[48:49], v169, v12
	v_lshlrev_b32_e32 v136, 6, v1
	v_or_b32_e32 v10, 0x800, v8
	v_or_b32_e32 v12, 0xc00, v8
	v_or_b32_e32 v14, 0x1000, v8
	v_or_b32_e32 v16, 0x1400, v8
	v_or_b32_e32 v18, 0x1800, v8
	v_or_b32_e32 v20, 0x1c00, v8
	v_lshlrev_b32_e32 v1, 7, v97
	s_waitcnt vmcnt(0)
	v_lshl_add_u64 v[38:39], v[22:23], 0, s[0:1]
	s_add_u32 s88, s68, 0x18c3d000
	v_lshl_add_u64 v[22:23], s[68:69], 0, v[4:5]
	s_mov_b64 s[0:1], 0x52bd000
	v_readlane_b32 s10, v251, 39
	v_readlane_b32 s11, v251, 40
	v_lshlrev_b32_e32 v44, 1, v0
	v_mbcnt_lo_u32_b32 v0, -1, 0
	v_add_u32_e32 v103, 0x90, v101
	v_add_u32_e32 v104, 0x110, v102
	v_add_u32_e32 v105, 0x120, v101
	v_add_u32_e32 v106, 0x220, v102
	v_add_u32_e32 v107, 0x1b0, v101
	v_add_u32_e32 v108, 0x330, v102
	v_add_u32_e32 v109, 0x240, v101
	v_add_u32_e32 v110, 0x440, v102
	v_add_u32_e32 v111, 0x2d0, v101
	v_add_u32_e32 v112, 0x550, v102
	v_add_u32_e32 v113, 0x360, v101
	v_add_u32_e32 v114, 0x660, v102
	v_add_u32_e32 v116, 0x770, v102
	v_add_u32_e32 v118, 0x880, v102
	v_add_u32_e32 v120, 0x990, v102
	v_add_u32_e32 v122, 0xaa0, v102
	v_add_u32_e32 v124, 0xbb0, v102
	v_add_u32_e32 v126, 0xcc0, v102
	v_add_u32_e32 v128, 0xdd0, v102
	v_add_u32_e32 v130, 0xee0, v102
	v_cmp_gt_u32_e32 vcc, v9, v11
	v_writelane_b32 v250, s3, 3
	v_cmp_lt_u32_e64 s[50:51], v169, v13
	v_cmp_gt_u32_e64 s[52:53], v169, v13
	v_cmp_gt_u32_e64 s[54:55], v169, v11
	v_add_u32_e32 v133, 0x90, v132
	v_add_u32_e32 v134, 0x120, v132
	v_add_u32_e32 v135, 0x1b0, v132
	v_sub_u32_e32 v138, v137, v1
	v_add_u32_e32 v139, 0xd800, v131
	v_add_u32_e32 v140, 0xd840, v131
	s_addc_u32 s89, s69, 0
	s_lshl_b32 s76, s90, 1
	v_lshl_add_u64 v[40:41], v[22:23], 0, s[0:1]
	v_lshl_add_u64 v[42:43], s[10:11], 0, v[4:5]
	v_lshlrev_b32_e32 v46, 1, v2
	s_mov_b32 s72, 0xffff0000
	s_mov_b32 s73, 0xbfb8aa3b
	s_mov_b32 s2, 0x800000
	s_mov_b32 s3, 0x3f317217
	v_lshlrev_b32_e32 v48, 1, v6
	v_lshlrev_b32_e32 v50, 1, v8
	v_lshlrev_b32_e32 v52, 1, v10
	v_lshlrev_b32_e32 v54, 1, v12
	v_lshlrev_b32_e32 v56, 1, v14
	v_lshlrev_b32_e32 v58, 1, v16
	v_lshlrev_b32_e32 v60, 1, v18
	v_lshlrev_b32_e32 v62, 1, v20
	v_mbcnt_hi_u32_b32 v141, -1, v0
	v_mov_b32_e32 v142, 0x358637bd
	v_mov_b32_e32 v143, 0x41b17218
	s_mov_b32 s4, 0x7f800000
	v_cmp_gt_u32_e64 s[56:57], v169, v15
	v_cmp_lt_u32_e64 s[58:59], v169, v11
	v_readlane_b32 s9, v251, 38
	v_readlane_b32 s12, v251, 41
	v_readlane_b32 s13, v251, 42
	v_readlane_b32 s14, v251, 43
	v_readlane_b32 s15, v251, 44
	v_readlane_b32 s16, v251, 45
	v_readlane_b32 s17, v251, 46
	v_readlane_b32 s18, v251, 47
	v_readlane_b32 s19, v251, 48
	v_readlane_b32 s20, v251, 49
	v_readlane_b32 s21, v251, 50
	v_readlane_b32 s22, v251, 51
	v_readlane_b32 s23, v251, 52
	v_readfirstlane_b32 s98, v171
	s_nop 3
	s_cmp_lt_u32 s98, 4
	s_cbranch_scc1 .Lprio8_done
	s_setprio 1
.Lprio8_done:
	s_nop 0
	s_branch .LBB0_1321

; __device__ __forceinline__ void phase8(const Params& P, unsigned char* smem) {
;     ...
;     for (int base = blockIdx.x * 2; base < 2048; base += gridDim.x * 2) gla_c_item(P, base + hb, smem + hb * HALF_LDS);
.LBB0_1340:
	s_setprio 0
	s_nop 0
	s_nop 0
	s_nop 0
	s_nop 0
	s_nop 0
	s_nop 0
	s_nop 0
	s_nop 0
	s_nop 0
	v_readlane_b32 s88, v251, 54
	v_readlane_b32 s89, v251, 55
